# context-tile groups rebalanced to 128 first / 128 last (x-column tiles still all first)
# baseline (speedup 1.0000x reference)
.LBB0_218:
	v_readlane_b32 s8, v244, 2
	v_readlane_b32 s9, v244, 3
	s_add_u32 s11, s8, 0x3900000
	s_addc_u32 s12, s9, 0
	s_add_u32 s4, s8, 0x7900000
	s_addc_u32 s5, s9, 0
	v_writelane_b32 v244, s4, 4
	s_load_dwordx2 s[94:95], s[52:53], 0x10
	s_load_dwordx4 s[44:47], s[52:53], 0x48
	v_writelane_b32 v244, s5, 5
	s_add_u32 s4, s8, 0x15eb4000
	v_writelane_b32 v244, s4, 6
	s_addc_u32 s4, s9, 0
	v_writelane_b32 v244, s4, 7
	s_add_u32 s4, s8, 0x15ea0000
	v_writelane_b32 v244, s4, 8
	s_addc_u32 s4, s9, 0
	s_and_b32 s98, s2, 63
	s_cmp_lt_u32 s98, 51
	s_cselect_b32 s99, 1, 0
	s_cmp_lt_u32 s98, 13
	s_cselect_b32 s98, 1, 0
	s_and_b32 s100, s2, 1
	s_and_b32 s99, s99, s100
	s_or_b32 s98, s98, s99
	s_cmp_eq_u32 s98, 0
	v_writelane_b32 v244, s4, 9
	s_cselect_b64 s[4:5], -1, 0
	v_writelane_b32 v244, s4, 10
	s_cmp_lg_u32 s98, 0
	v_lshrrev_b32_e32 v1, 20, v0
	v_writelane_b32 v244, s5, 11
	s_cselect_b64 s[4:5], -1, 0
	v_writelane_b32 v244, s4, 12
	s_cmpk_lt_i32 s2, 0x100
	v_lshrrev_b32_e32 v0, 10, v0
	v_writelane_b32 v244, s5, 13
	s_cselect_b64 s[4:5], -1, 0
	v_writelane_b32 v244, s4, 14
	s_cmpk_lt_i32 s2, 0x500
	v_or_b32_e32 v0, v0, v1
	v_writelane_b32 v244, s5, 15
	s_cselect_b64 s[4:5], -1, 0
	v_writelane_b32 v244, s4, 16
	s_ashr_i32 s66, s2, 31
	s_ashr_i32 s67, s80, 31
	v_writelane_b32 v244, s5, 17
	s_lshr_b32 s4, s66, 29
	s_add_i32 s5, s2, s4
	s_ashr_i32 s4, s5, 3
	s_and_b32 s5, s5, -8
	s_sub_i32 s5, s2, s5
	s_cmp_lt_i32 s70, 0
	s_cselect_b64 s[6:7], -1, 0
	s_add_u32 s14, s68, 0x16370f00
	s_addc_u32 s15, s69, 0
	s_add_u32 s16, s68, 0x16371100
	s_addc_u32 s17, s69, 0
	s_add_u32 s58, s68, 0x16371200
	v_writelane_b32 v244, s6, 18
	s_addc_u32 s59, s69, 0
	s_mul_i32 s81, s81, s80
	v_writelane_b32 v244, s7, 19
	s_add_u32 s6, s68, 0x16371300
	s_addc_u32 s7, s69, 0
	v_writelane_b32 v244, s6, 20
	s_mov_b32 s93, 0
	v_mbcnt_lo_u32_b32 v1, -1, 0
	v_writelane_b32 v244, s7, 21
	s_add_u32 s6, s68, 0x16371400
	s_addc_u32 s7, s69, 0
	v_writelane_b32 v244, s6, 22
	v_mov_b32_e32 v145, 0
	v_mov_b32_e32 v176, 0x358637bd
	v_writelane_b32 v244, s7, 23
	s_add_u32 s6, s68, 0x16371500
	s_addc_u32 s7, s69, 0
	v_writelane_b32 v244, s6, 24
	v_mov_b32_e32 v177, 0x260
	v_mov_b32_e32 v178, 1
	v_writelane_b32 v244, s7, 25
	s_add_u32 s6, s68, 0x16371600
	s_addc_u32 s7, s69, 0
	v_writelane_b32 v244, s6, 26
	v_mov_b32_e32 v179, 0x3ecc95a3
	v_mbcnt_hi_u32_b32 v180, -1, v1
	v_writelane_b32 v244, s7, 27
	s_add_u32 s6, s68, 0x16371700
	s_addc_u32 s7, s69, 0
	v_writelane_b32 v244, s6, 28
	v_mov_b64_e32 v[146:147], 0x500
	v_mov_b64_e32 v[148:149], 0x4ff
	v_writelane_b32 v244, s7, 29
	s_add_u32 s6, s68, 0x16371800
	s_addc_u32 s7, s69, 0
	v_writelane_b32 v244, s6, 30
	v_mov_b32_e32 v181, 0x82
	v_mov_b32_e32 v182, 0x7f800000
	v_writelane_b32 v244, s7, 31
	s_add_u32 s6, s68, 0x16371900
	s_addc_u32 s7, s69, 0
	s_add_u32 s34, s68, 0x16371a00
	s_addc_u32 s35, s69, 0
	s_add_u32 s36, s68, 0x16371b00
	s_addc_u32 s37, s69, 0
	s_add_u32 s18, s68, 0x16371c00
	s_addc_u32 s19, s69, 0
	s_add_u32 s20, s68, 0x16371d00
	s_addc_u32 s21, s69, 0
	s_add_u32 s22, s68, 0x16371e00
	s_addc_u32 s23, s69, 0
	s_add_u32 s24, s68, 0x16371f00
	s_addc_u32 s25, s69, 0
	s_add_u32 s26, s68, 0x16372000
	s_addc_u32 s27, s69, 0
	v_writelane_b32 v244, s6, 32
	s_cmp_eq_u32 s33, 15
	v_mov_b32_e32 v183, 0x7fc00000
	v_writelane_b32 v244, s7, 33
	s_cselect_b64 s[6:7], -1, 0
	v_writelane_b32 v244, s6, 34
	s_cmp_eq_u32 s33, 14
	v_mov_b32_e32 v184, 0xff800000
	v_writelane_b32 v244, s7, 35
	s_cselect_b64 s[6:7], -1, 0
	v_writelane_b32 v244, s6, 36
	s_cmp_eq_u32 s33, 13
	v_mov_b32_e32 v185, 0xc00
	v_writelane_b32 v244, s7, 37
	s_cselect_b64 s[6:7], -1, 0
	v_writelane_b32 v244, s6, 38
	s_cmp_eq_u32 s33, 12
	v_mov_b32_e32 v186, 0x800
	v_writelane_b32 v244, s7, 39
	s_cselect_b64 s[6:7], -1, 0
	v_writelane_b32 v244, s6, 40
	s_cmp_eq_u32 s33, 11
	v_mov_b32_e32 v187, 0x400
	v_writelane_b32 v244, s7, 41
	s_cselect_b64 s[6:7], -1, 0
	v_writelane_b32 v244, s6, 42
	s_cmp_eq_u32 s33, 10
	v_mov_b64_e32 v[150:151], 0x200
	v_writelane_b32 v244, s7, 43
	s_cselect_b64 s[6:7], -1, 0
	v_writelane_b32 v244, s6, 44
	s_cmp_eq_u32 s33, 9
	v_mov_b64_e32 v[152:153], 0x1ff
	v_writelane_b32 v244, s7, 45
	s_cselect_b64 s[6:7], -1, 0
	v_writelane_b32 v244, s6, 46
	s_cmp_eq_u32 s33, 8
	v_mov_b64_e32 v[154:155], 0x15ec4800
	v_writelane_b32 v244, s7, 47
	s_cselect_b64 s[6:7], -1, 0
	v_writelane_b32 v244, s6, 48
	s_cmp_eq_u32 s33, 7
	s_mov_b32 s84, 0x66666667
	v_writelane_b32 v244, s7, 49
	s_cselect_b64 s[6:7], -1, 0
	v_writelane_b32 v244, s6, 50
	s_cmp_eq_u32 s33, 6
	s_movk_i32 s62, 0x2800
	v_writelane_b32 v244, s7, 51
	s_cselect_b64 s[6:7], -1, 0
	v_writelane_b32 v244, s6, 52
	s_cmp_eq_u32 s33, 5
	s_mov_b32 s63, 0x10000
	v_writelane_b32 v244, s7, 53
	s_cselect_b64 s[6:7], -1, 0
	v_writelane_b32 v244, s6, 54
	s_cmp_eq_u32 s33, 4
	s_mov_b32 s30, 0x20000
	v_writelane_b32 v244, s7, 55
	s_cselect_b64 s[6:7], -1, 0
	v_writelane_b32 v244, s6, 56
	s_cmp_eq_u32 s33, 3
	s_movk_i32 s78, 0xffb0
	v_writelane_b32 v244, s7, 57
	s_cselect_b64 s[6:7], -1, 0
	v_writelane_b32 v244, s6, 58
	s_cmp_eq_u32 s33, 2
	s_mov_b32 s79, 0xf800000
	v_writelane_b32 v244, s7, 59
	s_cselect_b64 s[6:7], -1, 0
	v_writelane_b32 v244, s6, 60
	s_cmp_eq_u32 s33, 1
	s_movk_i32 s74, 0x1000
	v_writelane_b32 v244, s7, 61
	s_cselect_b64 s[6:7], -1, 0
	v_writelane_b32 v244, s6, 62
	s_cmp_eq_u32 s33, 0
	s_movk_i32 s75, 0xff3f
	v_writelane_b32 v244, s7, 63
	s_cselect_b64 s[6:7], -1, 0
	v_writelane_b32 v243, s6, 0
	s_movk_i32 s88, 0x5e
	s_mov_b32 s89, 0x11b80000
	v_writelane_b32 v243, s7, 1
	s_lshl_b32 s6, s33, 8
	s_add_u32 s0, s0, s6
	s_addc_u32 s1, s1, 0
	s_add_u32 s6, s0, 0x1400
	s_addc_u32 s7, s1, 0
	v_writelane_b32 v243, s6, 2
	s_add_u32 s0, s0, 0x2400
	s_addc_u32 s1, s1, 0
	v_writelane_b32 v243, s7, 3
	v_writelane_b32 v243, s0, 4
	s_movk_i32 s86, 0xfe7f
	s_movk_i32 s31, 0x4100
	v_writelane_b32 v243, s1, 5
	s_add_u32 s0, s68, 0x16374100
	s_addc_u32 s1, s69, 0
	v_writelane_b32 v243, s0, 6
	s_mov_b64 s[60:61], 0x80
	s_mov_b32 s96, s93
	v_writelane_b32 v243, s1, 7
	s_add_u32 s0, s68, 0x16374200
	s_addc_u32 s1, s69, 0
	v_writelane_b32 v243, s0, 8
	s_ashr_i32 s90, s80, 4
	s_ashr_i32 s40, s2, 4
	v_writelane_b32 v243, s1, 9
	s_and_b32 s0, s2, 15
	s_cmpk_lt_i32 s40, 0x82
	s_cselect_b64 s[6:7], -1, 0
	v_writelane_b32 v243, s6, 10
	s_lshl_b32 s1, s0, 14
	s_nop 0
	v_writelane_b32 v243, s7, 11
	v_writelane_b32 v243, s1, 12
	s_lshl_b32 s1, s0, 6
	v_writelane_b32 v243, s1, 13
	s_waitcnt lgkmcnt(0)
	s_mov_b64 s[6:7], s[46:47]
	v_writelane_b32 v243, s4, 14
	s_lshl_b32 s1, s0, 8
	s_add_u32 s38, s44, s1
	v_writelane_b32 v243, s5, 15
	v_writelane_b32 v243, s6, 16
	v_writelane_b32 v243, s7, 17
	s_addc_u32 s39, s45, 0
	s_lshl_b32 s1, s40, 7
	v_writelane_b32 v243, s38, 18
	s_cmp_lt_i32 s40, 2
	s_movk_i32 s6, 0x4100
	v_writelane_b32 v243, s39, 19
	s_cselect_b32 s6, 0x100, s6
	v_writelane_b32 v243, s6, 20
	s_cselect_b32 s6, 0, 0x100
	v_writelane_b32 v243, s6, 21
	v_writelane_b32 v243, s1, 22
	s_add_i32 s1, s1, -2
	v_writelane_b32 v243, s1, 23
	s_add_u32 s1, s68, 0x16370d40
	v_writelane_b32 v243, s1, 24
	s_addc_u32 s1, s69, 0
	s_cmp_lt_i32 s2, 64
	v_writelane_b32 v243, s1, 25
	s_cselect_b64 s[6:7], -1, 0
	s_add_u32 s13, s8, 0x11c80000
	v_writelane_b32 v243, s6, 26
	s_addc_u32 s33, s9, 0
	s_add_u32 s1, s8, 0x2800000
	v_writelane_b32 v243, s7, 27
	v_writelane_b32 v243, s1, 28
	s_addc_u32 s1, s9, 0
	s_add_u32 s38, s8, 0x16374d00
	s_addc_u32 s39, s9, 0
	s_cmpk_lt_i32 s2, 0x200
	v_writelane_b32 v243, s1, 29
	s_cselect_b64 s[6:7], -1, 0
	v_writelane_b32 v243, s6, 30
	s_lshl_b32 s1, s5, 6
	s_lshl_b32 s9, s2, 3
	s_lshl_b32 s10, s80, 3
	v_writelane_b32 v243, s7, 31
	s_cmp_lt_i32 s5, 0
	s_movk_i32 s6, 0xa1
	s_cselect_b32 s6, s6, 0xa0
	s_mul_i32 s6, s5, s6
	s_mulk_i32 s5, 0x41
	s_cselect_b32 s1, s5, s1
	s_add_i32 s6, s6, s4
	s_mul_hi_i32 s5, s6, 0x66666667
	s_lshr_b32 s7, s5, 31
	s_ashr_i32 s5, s5, 6
	s_add_i32 s5, s5, s7
	s_mul_i32 s7, s5, 0xa0
	s_sub_i32 s6, s6, s7
	s_bfe_u32 s7, s6, 0x3001c
	s_add_i32 s7, s6, s7
	s_and_b32 s8, s7, 0xfff8
	s_sub_i32 s6, s6, s8
	s_lshl_b32 s5, s5, 3
	s_sext_i32_i16 s7, s7
	s_sext_i32_i16 s6, s6
	s_add_i32 s42, s5, s6
	s_lshr_b32 s6, s7, 3
	s_ashr_i32 s5, s7, 3
	s_bfe_i64 s[6:7], s[6:7], 0x100000
	v_writelane_b32 v243, s5, 32
	s_lshl_b64 s[6:7], s[6:7], 20
	v_writelane_b32 v243, s6, 33
	s_ashr_i32 s43, s42, 31
	s_nop 0
	v_writelane_b32 v243, s7, 34
	s_mov_b32 s6, s42
	v_writelane_b32 v243, s6, 35
	s_nop 1
	v_writelane_b32 v243, s7, 36
	s_lshl_b64 s[6:7], s[42:43], 20
	s_add_u32 s6, s11, s6
	v_writelane_b32 v243, s11, 37
	s_addc_u32 s7, s12, s7
	v_writelane_b32 v243, s12, 38
	s_add_u32 s42, s6, 0x80000
	v_writelane_b32 v243, s6, 39
	s_addc_u32 s43, s7, 0
	s_add_i32 s1, s1, s4
	s_ashr_i32 s4, s1, 31
	s_lshr_b32 s4, s4, 26
	s_add_i32 s4, s1, s4
	s_and_b32 s5, s4, 0xffc0
	s_sub_i32 s1, s1, s5
	s_bfe_i32 s5, s1, 0x80000
	s_bfe_u32 s5, s5, 0x3000c
	s_add_i32 s5, s1, s5
	v_writelane_b32 v243, s7, 40
	s_and_b32 s6, s5, 0xf8
	s_sub_i32 s1, s1, s6
	s_ashr_i32 s4, s4, 6
	s_bfe_i32 s5, s5, 0x80000
	s_lshl_b32 s4, s4, 3
	s_sext_i32_i16 s5, s5
	s_sext_i32_i8 s1, s1
	v_writelane_b32 v243, s42, 41
	s_add_i32 s6, s4, s1
	s_lshr_b32 s4, s5, 3
	v_writelane_b32 v243, s43, 42
	s_ashr_i32 s1, s5, 3
	s_bfe_i64 s[4:5], s[4:5], 0x100000
	v_writelane_b32 v243, s1, 43
	s_lshl_b64 s[4:5], s[4:5], 20
	v_writelane_b32 v243, s4, 44
	s_ashr_i32 s7, s6, 31
	s_movk_i32 s1, 0x3ff
	v_writelane_b32 v243, s5, 45
	s_mov_b32 s4, s6
	v_writelane_b32 v243, s4, 46
	v_and_or_b32 v0, v0, s1, v175
	s_mul_i32 s1, s81, s3
	v_writelane_b32 v243, s5, 47
	s_lshl_b64 s[4:5], s[6:7], 20
	v_writelane_b32 v243, s13, 48
	s_add_u32 s4, s13, s4
	v_writelane_b32 v243, s33, 49
	s_addc_u32 s5, s33, s5
	v_writelane_b32 v243, s1, 50
	s_add_u32 s6, s4, 0x80000
	v_writelane_b32 v243, s4, 51
	s_addc_u32 s7, s5, 0
	s_ashr_i32 s41, s40, 31
	v_writelane_b32 v243, s5, 52
	s_lshl_b32 s3, s0, 9
	s_lshl_b64 s[0:1], s[40:41], 13
	v_writelane_b32 v243, s6, 53
	s_or_b32 s0, s0, s3
	s_add_u32 s0, s0, 0x16064c40
	v_writelane_b32 v243, s7, 54
	v_writelane_b32 v243, s0, 55
	s_addc_u32 s0, s1, 0
	v_writelane_b32 v243, s0, 56
	s_mov_b32 s0, s40
	v_writelane_b32 v243, s0, 57
	s_load_dwordx4 s[4:7], s[52:53], 0x98
	s_ashr_i32 s91, s90, 31
	v_writelane_b32 v243, s1, 58
	s_add_i32 s0, s40, s90
	v_writelane_b32 v243, s0, 59
	s_lshl_b32 s0, s0, 7
	v_writelane_b32 v243, s0, 60
	s_lshl_b32 s0, s2, 5
	v_writelane_b32 v243, s0, 61
	v_writelane_b32 v243, s9, 62
	s_add_i32 s0, s9, s10
	v_writelane_b32 v243, s0, 63
	s_add_i32 s0, 0, 0x20ff0
	v_writelane_b32 v242, s0, 0
	s_add_i32 s0, 0, 0x20ff4
	v_writelane_b32 v242, s0, 1
	s_add_i32 s0, 0, 0x1ec80
	v_writelane_b32 v242, s0, 2
	s_add_i32 s0, 0, 0x11c80
	v_writelane_b32 v242, s0, 3
	s_add_i32 s0, 0, 0x1a480
	v_writelane_b32 v242, s0, 4
	s_add_i32 s0, 0, 0x17800
	v_writelane_b32 v242, s0, 5
	v_cmp_eq_u32_e64 s[0:1], 0, v0
	s_ashr_i32 s11, s10, 31
	s_lshl_b32 s85, s90, 7
	v_writelane_b32 v242, s0, 6
	s_lshl_b32 s87, s80, 5
	s_mov_b32 s81, 0x30000
	v_writelane_b32 v242, s1, 7
	s_load_dwordx2 s[0:1], s[52:53], 0x58
	s_movk_i32 s3, 0x2000
	s_add_i32 s33, 0, 0x20fe0
	s_waitcnt lgkmcnt(0)
	v_writelane_b32 v242, s0, 8
	s_nop 1
	v_writelane_b32 v242, s1, 9
	s_load_dwordx2 s[0:1], s[52:53], 0x68
	s_waitcnt lgkmcnt(0)
	v_writelane_b32 v242, s0, 10
	s_nop 1
	v_writelane_b32 v242, s1, 11
	s_load_dwordx2 s[0:1], s[52:53], 0xb8
	s_waitcnt lgkmcnt(0)
	v_writelane_b32 v242, s0, 12
	s_nop 1
	v_writelane_b32 v242, s1, 13
	s_lshl_b64 s[0:1], s[90:91], 13
	v_writelane_b32 v242, s0, 14
	s_nop 1
	v_writelane_b32 v242, s1, 15
	s_lshl_b64 s[0:1], s[90:91], 12
	v_writelane_b32 v242, s0, 16
	s_mov_b32 s91, 0x40000
	s_nop 0
	v_writelane_b32 v242, s1, 17
	s_lshl_b64 s[0:1], s[10:11], 2
	v_writelane_b32 v242, s0, 18
	s_nop 1
	v_writelane_b32 v242, s1, 19
	v_writelane_b32 v242, s10, 20
	s_lshl_b64 s[0:1], s[10:11], 12
	s_nop 0
	v_writelane_b32 v242, s11, 21
	v_writelane_b32 v242, s0, 22
	s_nop 1
	v_writelane_b32 v242, s1, 23
	s_load_dwordx2 s[0:1], s[52:53], 0xa8
	s_waitcnt lgkmcnt(0)
	v_writelane_b32 v242, s0, 24
	s_nop 1
	v_writelane_b32 v242, s1, 25
	v_writelane_b32 v242, s4, 26
	s_nop 1
	v_writelane_b32 v242, s5, 27
	v_writelane_b32 v242, s6, 28
	v_writelane_b32 v242, s7, 29
	v_writelane_b32 v242, s52, 30
	s_load_dwordx8 s[4:11], s[52:53], 0x78
	s_nop 0
	v_writelane_b32 v242, s53, 31
	s_waitcnt lgkmcnt(0)
	v_writelane_b32 v242, s4, 32
	s_nop 1
	v_writelane_b32 v242, s5, 33
	v_writelane_b32 v242, s6, 34
	v_writelane_b32 v242, s7, 35
	v_writelane_b32 v242, s8, 36
	v_writelane_b32 v242, s9, 37
	v_writelane_b32 v242, s10, 38
	v_writelane_b32 v242, s11, 39
	v_writelane_b32 v242, s14, 40
	s_mov_b64 s[10:11], -1
	s_nop 0
	v_writelane_b32 v242, s15, 41
	v_writelane_b32 v242, s16, 42
	s_nop 1
	v_writelane_b32 v242, s17, 43
	v_writelane_b32 v242, s58, 44
	s_nop 1
	v_writelane_b32 v242, s59, 45
	v_writelane_b32 v242, s87, 46
	s_branch .LBB0_222
